# P0 weight conversion (gain variants): both 16-element staging steps of an item issued together (32 W + 32 gain loads in flight, one wait per item), staging loop removed
# speedup vs baseline: 1.0051x; 1.0051x over previous
; __device__ __forceinline__ void conv_item(const float* W, int K, int N, bf16* WT, const float* gain, int mapmode, bool f16, LAS float* scr, int item, int lane) {
;     ...
; #pragma unroll 16
;     for (int i = 0; i < 32; ++i) { const int kk = 2 * i + (lane >> 5); float v = __builtin_nontemporal_load(W + (size_t)(k0 + kk) * N + n0 + (lane & 31)); if (gain) v *= gain[k0 + kk]; scr[kk * 33 + (lane & 31)] = v; }
;     asm volatile("s_waitcnt lgkmcnt(0)" ::: "memory");
.LBB0_11:
	v_add_u32_e32 v26, s29, v22
	v_mad_i64_i32 v[28:29], s[40:41], v26, s23, v[20:21]
	global_load_dword v28, v[28:29], off nt
	v_ashrrev_i32_e32 v27, 31, v26
	v_add_u32_e32 v33, 2, v26
	v_mad_i64_i32 v[36:37], s[40:41], v33, s23, v[20:21]
	global_load_dword v33, v[36:37], off nt
	v_add_u32_e32 v40, 4, v26
	v_mad_i64_i32 v[40:41], s[40:41], v40, s23, v[20:21]
	global_load_dword v40, v[40:41], off nt
	v_add_u32_e32 v43, 6, v26
	v_mad_i64_i32 v[66:67], s[40:41], v43, s23, v[20:21]
	global_load_dword v43, v[66:67], off nt
	v_add_u32_e32 v70, 8, v26
	v_mad_i64_i32 v[70:71], s[40:41], v70, s23, v[20:21]
	global_load_dword v70, v[70:71], off nt
	v_add_u32_e32 v73, 10, v26
	v_mad_i64_i32 v[76:77], s[40:41], v73, s23, v[20:21]
	global_load_dword v73, v[76:77], off nt
	v_add_u32_e32 v80, 12, v26
	v_mad_i64_i32 v[80:81], s[40:41], v80, s23, v[20:21]
	global_load_dword v80, v[80:81], off nt
	v_add_u32_e32 v99, 14, v26
	v_mad_i64_i32 v[102:103], s[40:41], v99, s23, v[20:21]
	global_load_dword v99, v[102:103], off nt
	v_add_u32_e32 v106, 16, v26
	v_mad_i64_i32 v[106:107], s[40:41], v106, s23, v[20:21]
	global_load_dword v106, v[106:107], off nt
	v_add_u32_e32 v109, 18, v26
	v_mad_i64_i32 v[112:113], s[40:41], v109, s23, v[20:21]
	global_load_dword v109, v[112:113], off nt
	v_add_u32_e32 v116, 20, v26
	v_mad_i64_i32 v[116:117], s[40:41], v116, s23, v[20:21]
	global_load_dword v116, v[116:117], off nt
	v_add_u32_e32 v119, 22, v26
	v_mad_i64_i32 v[122:123], s[40:41], v119, s23, v[20:21]
	global_load_dword v119, v[122:123], off nt
	v_add_u32_e32 v126, 24, v26
	v_mad_i64_i32 v[126:127], s[40:41], v126, s23, v[20:21]
	global_load_dword v126, v[126:127], off nt
	v_add_u32_e32 v129, 26, v26
	v_mad_i64_i32 v[132:133], s[40:41], v129, s23, v[20:21]
	global_load_dword v129, v[132:133], off nt
	v_add_u32_e32 v136, 28, v26
	v_mad_i64_i32 v[136:137], s[40:41], v136, s23, v[20:21]
	global_load_dword v136, v[136:137], off nt
	v_add_u32_e32 v138, 30, v26
	v_mad_i64_i32 v[138:139], s[40:41], v138, s23, v[20:21]
	global_load_dword v138, v[138:139], off nt
	s_and_b64 vcc, exec, s[4:5]
	s_cbranch_vccnz .Lp0w0_a
	v_lshl_add_u64 v[30:31], v[26:27], 2, s[16:17]
	global_load_dword v27, v[30:31], off
	global_load_dword v34, v[24:25], off offset:-112
	global_load_dword v39, v[24:25], off offset:-104
	global_load_dword v44, v[24:25], off offset:-96
	global_load_dword v69, v[24:25], off offset:-88
	global_load_dword v74, v[24:25], off offset:-80
	global_load_dword v79, v[24:25], off offset:-72
	global_load_dword v100, v[24:25], off offset:-64
	global_load_dword v105, v[24:25], off offset:-56
	global_load_dword v110, v[24:25], off offset:-48
	global_load_dword v115, v[24:25], off offset:-40
	global_load_dword v120, v[24:25], off offset:-32
	global_load_dword v125, v[24:25], off offset:-24
	global_load_dword v130, v[24:25], off offset:-16
	global_load_dword v135, v[24:25], off offset:-8
	global_load_dword v139, v[24:25], off
; __device__ __forceinline__ void conv_item(const float* W, int K, int N, bf16* WT, const float* gain, int mapmode, bool f16, LAS float* scr, int item, int lane) {
;     ...
; #pragma unroll 16
;     for (int i = 0; i < 32; ++i) { const int kk = 2 * i + (lane >> 5); float v = __builtin_nontemporal_load(W + (size_t)(k0 + kk) * N + n0 + (lane & 31)); if (gain) v *= gain[k0 + kk]; scr[kk * 33 + (lane & 31)] = v; }
;     asm volatile("s_waitcnt lgkmcnt(0)" ::: "memory");
.Lp0w0_a:
	s_add_i32 s29, s29, 32
	v_lshl_add_u64 v[24:25], v[24:25], 0, s[8:9]
	v_add_u32_e32 v140, s29, v22
	v_mad_i64_i32 v[142:143], s[40:41], v140, s23, v[20:21]
	global_load_dword v142, v[142:143], off nt
	v_ashrrev_i32_e32 v141, 31, v140
	v_add_u32_e32 v147, 2, v140
	v_mad_i64_i32 v[150:151], s[40:41], v147, s23, v[20:21]
	global_load_dword v147, v[150:151], off nt
	v_add_u32_e32 v154, 4, v140
	v_mad_i64_i32 v[154:155], s[40:41], v154, s23, v[20:21]
	global_load_dword v154, v[154:155], off nt
	v_add_u32_e32 v157, 6, v140
	v_mad_i64_i32 v[160:161], s[40:41], v157, s23, v[20:21]
	global_load_dword v157, v[160:161], off nt
	v_add_u32_e32 v164, 8, v140
	v_mad_i64_i32 v[164:165], s[40:41], v164, s23, v[20:21]
	global_load_dword v164, v[164:165], off nt
	v_add_u32_e32 v167, 10, v140
	v_mad_i64_i32 v[170:171], s[40:41], v167, s23, v[20:21]
	global_load_dword v167, v[170:171], off nt
	v_add_u32_e32 v174, 12, v140
	v_mad_i64_i32 v[174:175], s[40:41], v174, s23, v[20:21]
	global_load_dword v174, v[174:175], off nt
	v_add_u32_e32 v177, 14, v140
	v_mad_i64_i32 v[180:181], s[40:41], v177, s23, v[20:21]
	global_load_dword v177, v[180:181], off nt
	v_add_u32_e32 v184, 16, v140
	v_mad_i64_i32 v[184:185], s[40:41], v184, s23, v[20:21]
	global_load_dword v184, v[184:185], off nt
	v_add_u32_e32 v187, 18, v140
	v_mad_i64_i32 v[190:191], s[40:41], v187, s23, v[20:21]
	global_load_dword v187, v[190:191], off nt
	v_add_u32_e32 v194, 20, v140
	v_mad_i64_i32 v[194:195], s[40:41], v194, s23, v[20:21]
	global_load_dword v194, v[194:195], off nt
	v_add_u32_e32 v197, 22, v140
	v_mad_i64_i32 v[200:201], s[40:41], v197, s23, v[20:21]
	global_load_dword v197, v[200:201], off nt
	v_add_u32_e32 v204, 24, v140
	v_mad_i64_i32 v[204:205], s[40:41], v204, s23, v[20:21]
	global_load_dword v204, v[204:205], off nt
	v_add_u32_e32 v207, 26, v140
	v_mad_i64_i32 v[210:211], s[40:41], v207, s23, v[20:21]
	global_load_dword v207, v[210:211], off nt
	v_add_u32_e32 v214, 28, v140
	v_mad_i64_i32 v[214:215], s[40:41], v214, s23, v[20:21]
	global_load_dword v214, v[214:215], off nt
	v_add_u32_e32 v216, 30, v140
	v_mad_i64_i32 v[216:217], s[40:41], v216, s23, v[20:21]
	global_load_dword v216, v[216:217], off nt
	s_and_b64 vcc, exec, s[4:5]
	s_cbranch_vccnz .Lp0w0_ng
	v_lshl_add_u64 v[144:145], v[140:141], 2, s[16:17]
	global_load_dword v141, v[144:145], off
	global_load_dword v148, v[24:25], off offset:-112
	global_load_dword v153, v[24:25], off offset:-104
	global_load_dword v158, v[24:25], off offset:-96
	global_load_dword v163, v[24:25], off offset:-88
	global_load_dword v168, v[24:25], off offset:-80
	global_load_dword v173, v[24:25], off offset:-72
	global_load_dword v178, v[24:25], off offset:-64
	global_load_dword v183, v[24:25], off offset:-56
	global_load_dword v188, v[24:25], off offset:-48
	global_load_dword v193, v[24:25], off offset:-40
	global_load_dword v198, v[24:25], off offset:-32
	global_load_dword v203, v[24:25], off offset:-24
	global_load_dword v208, v[24:25], off offset:-16
	global_load_dword v213, v[24:25], off offset:-8
	global_load_dword v217, v[24:25], off
	s_waitcnt vmcnt(0)
	v_mul_f32_e32 v28, v28, v27
	v_mul_f32_e32 v33, v33, v34
	v_mul_f32_e32 v40, v40, v39
	v_mul_f32_e32 v43, v43, v44
	v_mul_f32_e32 v70, v70, v69
	v_mul_f32_e32 v73, v73, v74
	v_mul_f32_e32 v80, v80, v79
	v_mul_f32_e32 v99, v99, v100
	v_mul_f32_e32 v106, v106, v105
	v_mul_f32_e32 v109, v109, v110
	v_mul_f32_e32 v116, v116, v115
	v_mul_f32_e32 v119, v119, v120
	v_mul_f32_e32 v126, v126, v125
	v_mul_f32_e32 v129, v129, v130
	v_mul_f32_e32 v136, v136, v135
	v_mul_f32_e32 v138, v138, v139
	v_mul_f32_e32 v142, v142, v141
	v_mul_f32_e32 v147, v147, v148
	v_mul_f32_e32 v154, v154, v153
	v_mul_f32_e32 v157, v157, v158
	v_mul_f32_e32 v164, v164, v163
	v_mul_f32_e32 v167, v167, v168
	v_mul_f32_e32 v174, v174, v173
	v_mul_f32_e32 v177, v177, v178
	v_mul_f32_e32 v184, v184, v183
	v_mul_f32_e32 v187, v187, v188
	v_mul_f32_e32 v194, v194, v193
	v_mul_f32_e32 v197, v197, v198
	v_mul_f32_e32 v204, v204, v203
	v_mul_f32_e32 v207, v207, v208
	v_mul_f32_e32 v214, v214, v213
	v_mul_f32_e32 v216, v216, v217
.Lp0w0_ng:
	s_waitcnt vmcnt(0)
	ds_write_b32 v23, v28
	ds_write_b32 v23, v33 offset:264
	ds_write_b32 v23, v40 offset:528
	ds_write_b32 v23, v43 offset:792
	ds_write_b32 v23, v70 offset:1056
	ds_write_b32 v23, v73 offset:1320
	ds_write_b32 v23, v80 offset:1584
	ds_write_b32 v23, v99 offset:1848
	ds_write_b32 v23, v106 offset:2112
	ds_write_b32 v23, v109 offset:2376
	ds_write_b32 v23, v116 offset:2640
	ds_write_b32 v23, v119 offset:2904
	ds_write_b32 v23, v126 offset:3168
	ds_write_b32 v23, v129 offset:3432
	ds_write_b32 v23, v136 offset:3696
	ds_write_b32 v23, v138 offset:3960
	v_add_u32_e32 v23, 0x1080, v23
	ds_write_b32 v23, v142
	ds_write_b32 v23, v147 offset:264
	ds_write_b32 v23, v154 offset:528
	ds_write_b32 v23, v157 offset:792
	ds_write_b32 v23, v164 offset:1056
	ds_write_b32 v23, v167 offset:1320
	ds_write_b32 v23, v174 offset:1584
	ds_write_b32 v23, v177 offset:1848
	ds_write_b32 v23, v184 offset:2112
	ds_write_b32 v23, v187 offset:2376
	ds_write_b32 v23, v194 offset:2640
	ds_write_b32 v23, v197 offset:2904
	ds_write_b32 v23, v204 offset:3168
	ds_write_b32 v23, v207 offset:3432
	ds_write_b32 v23, v214 offset:3696
	ds_write_b32 v23, v216 offset:3960
	v_add_u32_e32 v23, 0x1080, v23
	s_add_i32 s29, s29, 32
	v_lshl_add_u64 v[24:25], v[24:25], 0, s[8:9]
	s_branch .LBB0_8

; __device__ __forceinline__ void conv_item(const float* W, int K, int N, bf16* WT, const float* gain, int mapmode, bool f16, LAS float* scr, int item, int lane) {
;     ...
; #pragma unroll 16
;     for (int i = 0; i < 32; ++i) { const int kk = 2 * i + (lane >> 5); float v = __builtin_nontemporal_load(W + (size_t)(k0 + kk) * N + n0 + (lane & 31)); if (gain) v *= gain[k0 + kk]; scr[kk * 33 + (lane & 31)] = v; }
;     asm volatile("s_waitcnt lgkmcnt(0)" ::: "memory");
.LBB0_65:
	v_add_u32_e32 v28, s29, v24
	v_ashrrev_i32_e32 v29, 31, v28
	v_lshlrev_b64 v[30:31], 11, v[28:29]
	v_lshl_add_u64 v[30:31], v[22:23], 0, v[30:31]
	global_load_dword v30, v[30:31], off nt
	v_add_u32_e32 v40, 2, v28
	v_ashrrev_i32_e32 v41, 31, v40
	v_lshlrev_b64 v[40:41], 11, v[40:41]
	v_lshl_add_u64 v[40:41], v[22:23], 0, v[40:41]
	global_load_dword v37, v[40:41], off nt
	v_lshl_add_u64 v[38:39], s[36:37], 0, v[26:27]
	v_add_u32_e32 v44, 4, v28
	v_ashrrev_i32_e32 v45, 31, v44
	v_lshlrev_b64 v[44:45], 11, v[44:45]
	v_lshl_add_u64 v[44:45], v[22:23], 0, v[44:45]
	global_load_dword v44, v[44:45], off nt
	v_add_u32_e32 v100, 6, v28
	v_ashrrev_i32_e32 v101, 31, v100
	v_lshlrev_b64 v[100:101], 11, v[100:101]
	v_lshl_add_u64 v[100:101], v[22:23], 0, v[100:101]
	global_load_dword v99, v[100:101], off nt
	v_add_u32_e32 v104, 8, v28
	v_ashrrev_i32_e32 v105, 31, v104
	v_lshlrev_b64 v[104:105], 11, v[104:105]
	v_lshl_add_u64 v[104:105], v[22:23], 0, v[104:105]
	global_load_dword v104, v[104:105], off nt
	v_add_u32_e32 v108, 10, v28
	v_ashrrev_i32_e32 v109, 31, v108
	v_lshlrev_b64 v[108:109], 11, v[108:109]
	v_lshl_add_u64 v[108:109], v[22:23], 0, v[108:109]
	global_load_dword v107, v[108:109], off nt
	v_add_u32_e32 v112, 12, v28
	v_ashrrev_i32_e32 v113, 31, v112
	v_lshlrev_b64 v[112:113], 11, v[112:113]
	v_lshl_add_u64 v[112:113], v[22:23], 0, v[112:113]
	global_load_dword v112, v[112:113], off nt
	v_add_u32_e32 v116, 14, v28
	v_ashrrev_i32_e32 v117, 31, v116
	v_lshlrev_b64 v[116:117], 11, v[116:117]
	v_lshl_add_u64 v[116:117], v[22:23], 0, v[116:117]
	global_load_dword v115, v[116:117], off nt
	v_add_u32_e32 v120, 16, v28
	v_ashrrev_i32_e32 v121, 31, v120
	v_lshlrev_b64 v[120:121], 11, v[120:121]
	v_lshl_add_u64 v[120:121], v[22:23], 0, v[120:121]
	global_load_dword v120, v[120:121], off nt
	v_add_u32_e32 v124, 18, v28
	v_ashrrev_i32_e32 v125, 31, v124
	v_lshlrev_b64 v[124:125], 11, v[124:125]
	v_lshl_add_u64 v[124:125], v[22:23], 0, v[124:125]
	global_load_dword v123, v[124:125], off nt
	v_add_u32_e32 v128, 20, v28
	v_ashrrev_i32_e32 v129, 31, v128
	v_lshlrev_b64 v[128:129], 11, v[128:129]
	v_lshl_add_u64 v[128:129], v[22:23], 0, v[128:129]
	global_load_dword v128, v[128:129], off nt
	v_add_u32_e32 v132, 22, v28
	v_ashrrev_i32_e32 v133, 31, v132
	v_lshlrev_b64 v[132:133], 11, v[132:133]
	v_lshl_add_u64 v[132:133], v[22:23], 0, v[132:133]
	global_load_dword v131, v[132:133], off nt
	v_add_u32_e32 v136, 24, v28
	v_ashrrev_i32_e32 v137, 31, v136
	v_lshlrev_b64 v[136:137], 11, v[136:137]
	v_lshl_add_u64 v[136:137], v[22:23], 0, v[136:137]
	global_load_dword v136, v[136:137], off nt
	v_add_u32_e32 v140, 26, v28
	v_ashrrev_i32_e32 v141, 31, v140
	v_lshlrev_b64 v[140:141], 11, v[140:141]
	v_lshl_add_u64 v[140:141], v[22:23], 0, v[140:141]
	global_load_dword v139, v[140:141], off nt
	v_add_u32_e32 v144, 28, v28
	v_ashrrev_i32_e32 v145, 31, v144
	v_lshlrev_b64 v[144:145], 11, v[144:145]
	v_lshl_add_u64 v[144:145], v[22:23], 0, v[144:145]
	global_load_dword v144, v[144:145], off nt
	v_add_u32_e32 v146, 30, v28
	v_ashrrev_i32_e32 v147, 31, v146
	v_lshlrev_b64 v[146:147], 11, v[146:147]
	v_lshl_add_u64 v[146:147], v[22:23], 0, v[146:147]
	global_load_dword v146, v[146:147], off nt
	s_and_b64 vcc, exec, s[4:5]
	s_cbranch_vccnz .Lp0w1_a
	v_lshl_add_u64 v[32:33], v[28:29], 2, s[16:17]
	global_load_dword v29, v[32:33], off
	global_load_dword v40, v[38:39], off offset:-112
	global_load_dword v43, v[38:39], off offset:-104
	global_load_dword v36, v[38:39], off offset:-96
	global_load_dword v103, v[38:39], off offset:-88
	global_load_dword v42, v[38:39], off offset:-80
	global_load_dword v111, v[38:39], off offset:-72
	global_load_dword v98, v[38:39], off offset:-64
	global_load_dword v119, v[38:39], off offset:-56
	global_load_dword v102, v[38:39], off offset:-48
	global_load_dword v127, v[38:39], off offset:-40
	global_load_dword v106, v[38:39], off offset:-32
	global_load_dword v135, v[38:39], off offset:-24
	global_load_dword v110, v[38:39], off offset:-16
	global_load_dword v143, v[38:39], off offset:-8
	global_load_dword v147, v[38:39], off
; __device__ __forceinline__ void conv_item(const float* W, int K, int N, bf16* WT, const float* gain, int mapmode, bool f16, LAS float* scr, int item, int lane) {
;     ...
; #pragma unroll 16
;     for (int i = 0; i < 32; ++i) { const int kk = 2 * i + (lane >> 5); float v = __builtin_nontemporal_load(W + (size_t)(k0 + kk) * N + n0 + (lane & 31)); if (gain) v *= gain[k0 + kk]; scr[kk * 33 + (lane & 31)] = v; }
;     asm volatile("s_waitcnt lgkmcnt(0)" ::: "memory");
.Lp0w1_a:
	s_add_i32 s29, s29, 32
	s_add_u32 s36, s36, 0x80
	s_addc_u32 s37, s37, 0
	v_add_u32_e32 v148, s29, v24
	v_ashrrev_i32_e32 v149, 31, v148
	v_lshlrev_b64 v[150:151], 11, v[148:149]
	v_lshl_add_u64 v[150:151], v[22:23], 0, v[150:151]
	global_load_dword v150, v[150:151], off nt
	v_add_u32_e32 v158, 2, v148
	v_ashrrev_i32_e32 v159, 31, v158
	v_lshlrev_b64 v[158:159], 11, v[158:159]
	v_lshl_add_u64 v[158:159], v[22:23], 0, v[158:159]
	global_load_dword v155, v[158:159], off nt
	v_lshl_add_u64 v[156:157], s[36:37], 0, v[26:27]
	v_add_u32_e32 v162, 4, v148
	v_ashrrev_i32_e32 v163, 31, v162
	v_lshlrev_b64 v[162:163], 11, v[162:163]
	v_lshl_add_u64 v[162:163], v[22:23], 0, v[162:163]
	global_load_dword v162, v[162:163], off nt
	v_add_u32_e32 v166, 6, v148
	v_ashrrev_i32_e32 v167, 31, v166
	v_lshlrev_b64 v[166:167], 11, v[166:167]
	v_lshl_add_u64 v[166:167], v[22:23], 0, v[166:167]
	global_load_dword v165, v[166:167], off nt
	v_add_u32_e32 v170, 8, v148
	v_ashrrev_i32_e32 v171, 31, v170
	v_lshlrev_b64 v[170:171], 11, v[170:171]
	v_lshl_add_u64 v[170:171], v[22:23], 0, v[170:171]
	global_load_dword v170, v[170:171], off nt
	v_add_u32_e32 v174, 10, v148
	v_ashrrev_i32_e32 v175, 31, v174
	v_lshlrev_b64 v[174:175], 11, v[174:175]
	v_lshl_add_u64 v[174:175], v[22:23], 0, v[174:175]
	global_load_dword v173, v[174:175], off nt
	v_add_u32_e32 v178, 12, v148
	v_ashrrev_i32_e32 v179, 31, v178
	v_lshlrev_b64 v[178:179], 11, v[178:179]
	v_lshl_add_u64 v[178:179], v[22:23], 0, v[178:179]
	global_load_dword v178, v[178:179], off nt
	v_add_u32_e32 v182, 14, v148
	v_ashrrev_i32_e32 v183, 31, v182
	v_lshlrev_b64 v[182:183], 11, v[182:183]
	v_lshl_add_u64 v[182:183], v[22:23], 0, v[182:183]
	global_load_dword v181, v[182:183], off nt
	v_add_u32_e32 v186, 16, v148
	v_ashrrev_i32_e32 v187, 31, v186
	v_lshlrev_b64 v[186:187], 11, v[186:187]
	v_lshl_add_u64 v[186:187], v[22:23], 0, v[186:187]
	global_load_dword v186, v[186:187], off nt
	v_add_u32_e32 v190, 18, v148
	v_ashrrev_i32_e32 v191, 31, v190
	v_lshlrev_b64 v[190:191], 11, v[190:191]
	v_lshl_add_u64 v[190:191], v[22:23], 0, v[190:191]
	global_load_dword v189, v[190:191], off nt
	v_add_u32_e32 v194, 20, v148
	v_ashrrev_i32_e32 v195, 31, v194
	v_lshlrev_b64 v[194:195], 11, v[194:195]
	v_lshl_add_u64 v[194:195], v[22:23], 0, v[194:195]
	global_load_dword v194, v[194:195], off nt
	v_add_u32_e32 v198, 22, v148
	v_ashrrev_i32_e32 v199, 31, v198
	v_lshlrev_b64 v[198:199], 11, v[198:199]
	v_lshl_add_u64 v[198:199], v[22:23], 0, v[198:199]
	global_load_dword v197, v[198:199], off nt
	v_add_u32_e32 v202, 24, v148
	v_ashrrev_i32_e32 v203, 31, v202
	v_lshlrev_b64 v[202:203], 11, v[202:203]
	v_lshl_add_u64 v[202:203], v[22:23], 0, v[202:203]
	global_load_dword v202, v[202:203], off nt
	v_add_u32_e32 v206, 26, v148
	v_ashrrev_i32_e32 v207, 31, v206
	v_lshlrev_b64 v[206:207], 11, v[206:207]
	v_lshl_add_u64 v[206:207], v[22:23], 0, v[206:207]
	global_load_dword v205, v[206:207], off nt
	v_add_u32_e32 v210, 28, v148
	v_ashrrev_i32_e32 v211, 31, v210
	v_lshlrev_b64 v[210:211], 11, v[210:211]
	v_lshl_add_u64 v[210:211], v[22:23], 0, v[210:211]
	global_load_dword v210, v[210:211], off nt
	v_add_u32_e32 v212, 30, v148
	v_ashrrev_i32_e32 v213, 31, v212
	v_lshlrev_b64 v[212:213], 11, v[212:213]
	v_lshl_add_u64 v[212:213], v[22:23], 0, v[212:213]
	global_load_dword v212, v[212:213], off nt
	s_and_b64 vcc, exec, s[4:5]
	s_cbranch_vccnz .Lp0w1_ng
	v_lshl_add_u64 v[152:153], v[148:149], 2, s[16:17]
	global_load_dword v149, v[152:153], off
	global_load_dword v158, v[156:157], off offset:-112
	global_load_dword v161, v[156:157], off offset:-104
	global_load_dword v114, v[156:157], off offset:-96
	global_load_dword v169, v[156:157], off offset:-88
	global_load_dword v118, v[156:157], off offset:-80
	global_load_dword v177, v[156:157], off offset:-72
	global_load_dword v122, v[156:157], off offset:-64
	global_load_dword v185, v[156:157], off offset:-56
	global_load_dword v126, v[156:157], off offset:-48
	global_load_dword v193, v[156:157], off offset:-40
	global_load_dword v130, v[156:157], off offset:-32
	global_load_dword v201, v[156:157], off offset:-24
	global_load_dword v134, v[156:157], off offset:-16
	global_load_dword v209, v[156:157], off offset:-8
	global_load_dword v213, v[156:157], off
	s_waitcnt vmcnt(0)
	v_mul_f32_e32 v30, v30, v29
	v_mul_f32_e32 v37, v37, v40
	v_mul_f32_e32 v44, v44, v43
	v_mul_f32_e32 v99, v99, v36
	v_mul_f32_e32 v104, v104, v103
	v_mul_f32_e32 v107, v107, v42
	v_mul_f32_e32 v112, v112, v111
	v_mul_f32_e32 v115, v115, v98
	v_mul_f32_e32 v120, v120, v119
	v_mul_f32_e32 v123, v123, v102
	v_mul_f32_e32 v128, v128, v127
	v_mul_f32_e32 v131, v131, v106
	v_mul_f32_e32 v136, v136, v135
	v_mul_f32_e32 v139, v139, v110
	v_mul_f32_e32 v144, v144, v143
	v_mul_f32_e32 v146, v146, v147
	v_mul_f32_e32 v150, v150, v149
	v_mul_f32_e32 v155, v155, v158
	v_mul_f32_e32 v162, v162, v161
	v_mul_f32_e32 v165, v165, v114
	v_mul_f32_e32 v170, v170, v169
	v_mul_f32_e32 v173, v173, v118
	v_mul_f32_e32 v178, v178, v177
	v_mul_f32_e32 v181, v181, v122
	v_mul_f32_e32 v186, v186, v185
	v_mul_f32_e32 v189, v189, v126
	v_mul_f32_e32 v194, v194, v193
	v_mul_f32_e32 v197, v197, v130
	v_mul_f32_e32 v202, v202, v201
	v_mul_f32_e32 v205, v205, v134
	v_mul_f32_e32 v210, v210, v209
	v_mul_f32_e32 v212, v212, v213
.Lp0w1_ng:
	s_waitcnt vmcnt(0)
	ds_write_b32 v25, v30
	ds_write_b32 v25, v37 offset:264
	ds_write_b32 v25, v44 offset:528
	ds_write_b32 v25, v99 offset:792
	ds_write_b32 v25, v104 offset:1056
	ds_write_b32 v25, v107 offset:1320
	ds_write_b32 v25, v112 offset:1584
	ds_write_b32 v25, v115 offset:1848
	ds_write_b32 v25, v120 offset:2112
	ds_write_b32 v25, v123 offset:2376
	ds_write_b32 v25, v128 offset:2640
	ds_write_b32 v25, v131 offset:2904
	ds_write_b32 v25, v136 offset:3168
	ds_write_b32 v25, v139 offset:3432
	ds_write_b32 v25, v144 offset:3696
	ds_write_b32 v25, v146 offset:3960
	v_add_u32_e32 v25, 0x1080, v25
	ds_write_b32 v25, v150
	ds_write_b32 v25, v155 offset:264
	ds_write_b32 v25, v162 offset:528
	ds_write_b32 v25, v165 offset:792
	ds_write_b32 v25, v170 offset:1056
	ds_write_b32 v25, v173 offset:1320
	ds_write_b32 v25, v178 offset:1584
	ds_write_b32 v25, v181 offset:1848
	ds_write_b32 v25, v186 offset:2112
	ds_write_b32 v25, v189 offset:2376
	ds_write_b32 v25, v194 offset:2640
	ds_write_b32 v25, v197 offset:2904
	ds_write_b32 v25, v202 offset:3168
	ds_write_b32 v25, v205 offset:3432
	ds_write_b32 v25, v210 offset:3696
	ds_write_b32 v25, v212 offset:3960
	v_add_u32_e32 v25, 0x1080, v25
	s_add_i32 s29, s29, 32
	s_add_u32 s36, s36, 0x80
	s_addc_u32 s37, s37, 0
	s_branch .LBB0_62

; __device__ __forceinline__ void conv_item(const float* W, int K, int N, bf16* WT, const float* gain, int mapmode, bool f16, LAS float* scr, int item, int lane) {
;     ...
; #pragma unroll 16
;     for (int i = 0; i < 32; ++i) { const int kk = 2 * i + (lane >> 5); float v = __builtin_nontemporal_load(W + (size_t)(k0 + kk) * N + n0 + (lane & 31)); if (gain) v *= gain[k0 + kk]; scr[kk * 33 + (lane & 31)] = v; }
;     asm volatile("s_waitcnt lgkmcnt(0)" ::: "memory");
.LBB0_102:
	v_add_u32_e32 v28, s29, v24
	v_ashrrev_i32_e32 v29, 31, v28
	v_lshlrev_b64 v[30:31], 12, v[28:29]
	v_lshl_add_u64 v[30:31], v[22:23], 0, v[30:31]
	global_load_dword v30, v[30:31], off nt
	v_cndmask_b32_e64 v31, 0, 1, s[16:17]
	v_cmp_ne_u32_e64 s[4:5], 1, v31
	v_add_u32_e32 v40, 2, v28
	v_ashrrev_i32_e32 v41, 31, v40
	v_lshlrev_b64 v[40:41], 12, v[40:41]
	v_lshl_add_u64 v[40:41], v[22:23], 0, v[40:41]
	global_load_dword v37, v[40:41], off nt
	v_lshl_add_u64 v[38:39], s[36:37], 0, v[26:27]
	v_add_u32_e32 v44, 4, v28
	v_ashrrev_i32_e32 v45, 31, v44
	v_lshlrev_b64 v[44:45], 12, v[44:45]
	v_lshl_add_u64 v[44:45], v[22:23], 0, v[44:45]
	global_load_dword v44, v[44:45], off nt
	v_add_u32_e32 v100, 6, v28
	v_ashrrev_i32_e32 v101, 31, v100
	v_lshlrev_b64 v[100:101], 12, v[100:101]
	v_lshl_add_u64 v[100:101], v[22:23], 0, v[100:101]
	global_load_dword v99, v[100:101], off nt
	v_add_u32_e32 v104, 8, v28
	v_ashrrev_i32_e32 v105, 31, v104
	v_lshlrev_b64 v[104:105], 12, v[104:105]
	v_lshl_add_u64 v[104:105], v[22:23], 0, v[104:105]
	global_load_dword v104, v[104:105], off nt
	v_add_u32_e32 v108, 10, v28
	v_ashrrev_i32_e32 v109, 31, v108
	v_lshlrev_b64 v[108:109], 12, v[108:109]
	v_lshl_add_u64 v[108:109], v[22:23], 0, v[108:109]
	global_load_dword v107, v[108:109], off nt
	v_add_u32_e32 v112, 12, v28
	v_ashrrev_i32_e32 v113, 31, v112
	v_lshlrev_b64 v[112:113], 12, v[112:113]
	v_lshl_add_u64 v[112:113], v[22:23], 0, v[112:113]
	global_load_dword v112, v[112:113], off nt
	v_add_u32_e32 v116, 14, v28
	v_ashrrev_i32_e32 v117, 31, v116
	v_lshlrev_b64 v[116:117], 12, v[116:117]
	v_lshl_add_u64 v[116:117], v[22:23], 0, v[116:117]
	global_load_dword v115, v[116:117], off nt
	v_add_u32_e32 v120, 16, v28
	v_ashrrev_i32_e32 v121, 31, v120
	v_lshlrev_b64 v[120:121], 12, v[120:121]
	v_lshl_add_u64 v[120:121], v[22:23], 0, v[120:121]
	global_load_dword v120, v[120:121], off nt
	v_add_u32_e32 v124, 18, v28
	v_ashrrev_i32_e32 v125, 31, v124
	v_lshlrev_b64 v[124:125], 12, v[124:125]
	v_lshl_add_u64 v[124:125], v[22:23], 0, v[124:125]
	global_load_dword v123, v[124:125], off nt
	v_add_u32_e32 v128, 20, v28
	v_ashrrev_i32_e32 v129, 31, v128
	v_lshlrev_b64 v[128:129], 12, v[128:129]
	v_lshl_add_u64 v[128:129], v[22:23], 0, v[128:129]
	global_load_dword v128, v[128:129], off nt
	v_add_u32_e32 v132, 22, v28
	v_ashrrev_i32_e32 v133, 31, v132
	v_lshlrev_b64 v[132:133], 12, v[132:133]
	v_lshl_add_u64 v[132:133], v[22:23], 0, v[132:133]
	global_load_dword v131, v[132:133], off nt
	v_add_u32_e32 v136, 24, v28
	v_ashrrev_i32_e32 v137, 31, v136
	v_lshlrev_b64 v[136:137], 12, v[136:137]
	v_lshl_add_u64 v[136:137], v[22:23], 0, v[136:137]
	global_load_dword v136, v[136:137], off nt
	v_add_u32_e32 v140, 26, v28
	v_ashrrev_i32_e32 v141, 31, v140
	v_lshlrev_b64 v[140:141], 12, v[140:141]
	v_lshl_add_u64 v[140:141], v[22:23], 0, v[140:141]
	global_load_dword v139, v[140:141], off nt
	v_add_u32_e32 v144, 28, v28
	v_ashrrev_i32_e32 v145, 31, v144
	v_lshlrev_b64 v[144:145], 12, v[144:145]
	v_lshl_add_u64 v[144:145], v[22:23], 0, v[144:145]
	global_load_dword v144, v[144:145], off nt
	v_add_u32_e32 v146, 30, v28
	v_ashrrev_i32_e32 v147, 31, v146
	v_lshlrev_b64 v[146:147], 12, v[146:147]
	v_lshl_add_u64 v[146:147], v[22:23], 0, v[146:147]
	global_load_dword v146, v[146:147], off nt
	s_andn2_b64 vcc, exec, s[16:17]
	s_cbranch_vccnz .Lp0w2_a
	v_lshl_add_u64 v[32:33], v[28:29], 2, s[12:13]
	global_load_dword v29, v[32:33], off
	global_load_dword v40, v[38:39], off offset:-112
	global_load_dword v43, v[38:39], off offset:-104
	global_load_dword v36, v[38:39], off offset:-96
	global_load_dword v103, v[38:39], off offset:-88
	global_load_dword v42, v[38:39], off offset:-80
	global_load_dword v111, v[38:39], off offset:-72
	global_load_dword v98, v[38:39], off offset:-64
	global_load_dword v119, v[38:39], off offset:-56
	global_load_dword v102, v[38:39], off offset:-48
	global_load_dword v127, v[38:39], off offset:-40
	global_load_dword v106, v[38:39], off offset:-32
	global_load_dword v135, v[38:39], off offset:-24
	global_load_dword v110, v[38:39], off offset:-16
	global_load_dword v143, v[38:39], off offset:-8
	global_load_dword v147, v[38:39], off
; __device__ __forceinline__ void conv_item(const float* W, int K, int N, bf16* WT, const float* gain, int mapmode, bool f16, LAS float* scr, int item, int lane) {
;     ...
; #pragma unroll 16
;     for (int i = 0; i < 32; ++i) { const int kk = 2 * i + (lane >> 5); float v = __builtin_nontemporal_load(W + (size_t)(k0 + kk) * N + n0 + (lane & 31)); if (gain) v *= gain[k0 + kk]; scr[kk * 33 + (lane & 31)] = v; }
.Lp0w2_a:
	s_add_i32 s29, s29, 32
	s_add_u32 s36, s36, 0x80
	s_addc_u32 s37, s37, 0
	v_add_u32_e32 v148, s29, v24
	v_ashrrev_i32_e32 v149, 31, v148
	v_lshlrev_b64 v[150:151], 12, v[148:149]
	v_lshl_add_u64 v[150:151], v[22:23], 0, v[150:151]
	global_load_dword v150, v[150:151], off nt
	v_cndmask_b32_e64 v151, 0, 1, s[16:17]
	v_cmp_ne_u32_e64 s[4:5], 1, v151
	v_add_u32_e32 v158, 2, v148
	v_ashrrev_i32_e32 v159, 31, v158
	v_lshlrev_b64 v[158:159], 12, v[158:159]
	v_lshl_add_u64 v[158:159], v[22:23], 0, v[158:159]
	global_load_dword v155, v[158:159], off nt
	v_lshl_add_u64 v[156:157], s[36:37], 0, v[26:27]
	v_add_u32_e32 v162, 4, v148
	v_ashrrev_i32_e32 v163, 31, v162
	v_lshlrev_b64 v[162:163], 12, v[162:163]
	v_lshl_add_u64 v[162:163], v[22:23], 0, v[162:163]
	global_load_dword v162, v[162:163], off nt
	v_add_u32_e32 v166, 6, v148
	v_ashrrev_i32_e32 v167, 31, v166
	v_lshlrev_b64 v[166:167], 12, v[166:167]
	v_lshl_add_u64 v[166:167], v[22:23], 0, v[166:167]
	global_load_dword v165, v[166:167], off nt
	v_add_u32_e32 v170, 8, v148
	v_ashrrev_i32_e32 v171, 31, v170
	v_lshlrev_b64 v[170:171], 12, v[170:171]
	v_lshl_add_u64 v[170:171], v[22:23], 0, v[170:171]
	global_load_dword v170, v[170:171], off nt
	v_add_u32_e32 v174, 10, v148
	v_ashrrev_i32_e32 v175, 31, v174
	v_lshlrev_b64 v[174:175], 12, v[174:175]
	v_lshl_add_u64 v[174:175], v[22:23], 0, v[174:175]
	global_load_dword v173, v[174:175], off nt
	v_add_u32_e32 v178, 12, v148
	v_ashrrev_i32_e32 v179, 31, v178
	v_lshlrev_b64 v[178:179], 12, v[178:179]
	v_lshl_add_u64 v[178:179], v[22:23], 0, v[178:179]
	global_load_dword v178, v[178:179], off nt
	v_add_u32_e32 v182, 14, v148
	v_ashrrev_i32_e32 v183, 31, v182
	v_lshlrev_b64 v[182:183], 12, v[182:183]
	v_lshl_add_u64 v[182:183], v[22:23], 0, v[182:183]
	global_load_dword v181, v[182:183], off nt
	v_add_u32_e32 v186, 16, v148
	v_ashrrev_i32_e32 v187, 31, v186
	v_lshlrev_b64 v[186:187], 12, v[186:187]
	v_lshl_add_u64 v[186:187], v[22:23], 0, v[186:187]
	global_load_dword v186, v[186:187], off nt
	v_add_u32_e32 v190, 18, v148
	v_ashrrev_i32_e32 v191, 31, v190
	v_lshlrev_b64 v[190:191], 12, v[190:191]
	v_lshl_add_u64 v[190:191], v[22:23], 0, v[190:191]
	global_load_dword v189, v[190:191], off nt
	v_add_u32_e32 v194, 20, v148
	v_ashrrev_i32_e32 v195, 31, v194
	v_lshlrev_b64 v[194:195], 12, v[194:195]
	v_lshl_add_u64 v[194:195], v[22:23], 0, v[194:195]
	global_load_dword v194, v[194:195], off nt
	v_add_u32_e32 v198, 22, v148
	v_ashrrev_i32_e32 v199, 31, v198
	v_lshlrev_b64 v[198:199], 12, v[198:199]
	v_lshl_add_u64 v[198:199], v[22:23], 0, v[198:199]
	global_load_dword v197, v[198:199], off nt
	v_add_u32_e32 v202, 24, v148
	v_ashrrev_i32_e32 v203, 31, v202
	v_lshlrev_b64 v[202:203], 12, v[202:203]
	v_lshl_add_u64 v[202:203], v[22:23], 0, v[202:203]
	global_load_dword v202, v[202:203], off nt
	v_add_u32_e32 v206, 26, v148
	v_ashrrev_i32_e32 v207, 31, v206
	v_lshlrev_b64 v[206:207], 12, v[206:207]
	v_lshl_add_u64 v[206:207], v[22:23], 0, v[206:207]
	global_load_dword v205, v[206:207], off nt
	v_add_u32_e32 v210, 28, v148
	v_ashrrev_i32_e32 v211, 31, v210
	v_lshlrev_b64 v[210:211], 12, v[210:211]
	v_lshl_add_u64 v[210:211], v[22:23], 0, v[210:211]
	global_load_dword v210, v[210:211], off nt
	v_add_u32_e32 v212, 30, v148
	v_ashrrev_i32_e32 v213, 31, v212
	v_lshlrev_b64 v[212:213], 12, v[212:213]
	v_lshl_add_u64 v[212:213], v[22:23], 0, v[212:213]
	global_load_dword v212, v[212:213], off nt
	s_andn2_b64 vcc, exec, s[16:17]
	s_cbranch_vccnz .Lp0w2_ng
	v_lshl_add_u64 v[152:153], v[148:149], 2, s[12:13]
	global_load_dword v149, v[152:153], off
	global_load_dword v158, v[156:157], off offset:-112
	global_load_dword v161, v[156:157], off offset:-104
	global_load_dword v114, v[156:157], off offset:-96
	global_load_dword v169, v[156:157], off offset:-88
	global_load_dword v118, v[156:157], off offset:-80
	global_load_dword v177, v[156:157], off offset:-72
	global_load_dword v122, v[156:157], off offset:-64
	global_load_dword v185, v[156:157], off offset:-56
	global_load_dword v126, v[156:157], off offset:-48
	global_load_dword v193, v[156:157], off offset:-40
	global_load_dword v130, v[156:157], off offset:-32
	global_load_dword v201, v[156:157], off offset:-24
	global_load_dword v134, v[156:157], off offset:-16
	global_load_dword v209, v[156:157], off offset:-8
	global_load_dword v213, v[156:157], off
	s_waitcnt vmcnt(0)
	v_mul_f32_e32 v30, v30, v29
	v_mul_f32_e32 v37, v37, v40
	v_mul_f32_e32 v44, v44, v43
	v_mul_f32_e32 v99, v99, v36
	v_mul_f32_e32 v104, v104, v103
	v_mul_f32_e32 v107, v107, v42
	v_mul_f32_e32 v112, v112, v111
	v_mul_f32_e32 v115, v115, v98
	v_mul_f32_e32 v120, v120, v119
	v_mul_f32_e32 v123, v123, v102
	v_mul_f32_e32 v128, v128, v127
	v_mul_f32_e32 v131, v131, v106
	v_mul_f32_e32 v136, v136, v135
	v_mul_f32_e32 v139, v139, v110
	v_mul_f32_e32 v144, v144, v143
	v_mul_f32_e32 v146, v146, v147
	v_mul_f32_e32 v150, v150, v149
	v_mul_f32_e32 v155, v155, v158
	v_mul_f32_e32 v162, v162, v161
	v_mul_f32_e32 v165, v165, v114
	v_mul_f32_e32 v170, v170, v169
	v_mul_f32_e32 v173, v173, v118
	v_mul_f32_e32 v178, v178, v177
	v_mul_f32_e32 v181, v181, v122
	v_mul_f32_e32 v186, v186, v185
	v_mul_f32_e32 v189, v189, v126
	v_mul_f32_e32 v194, v194, v193
	v_mul_f32_e32 v197, v197, v130
	v_mul_f32_e32 v202, v202, v201
	v_mul_f32_e32 v205, v205, v134
	v_mul_f32_e32 v210, v210, v209
	v_mul_f32_e32 v212, v212, v213

; __device__ __forceinline__ void conv_item(const float* W, int K, int N, bf16* WT, const float* gain, int mapmode, bool f16, LAS float* scr, int item, int lane) {
;     ...
; #pragma unroll 16
;     for (int i = 0; i < 32; ++i) { const int kk = 2 * i + (lane >> 5); float v = __builtin_nontemporal_load(W + (size_t)(k0 + kk) * N + n0 + (lane & 31)); if (gain) v *= gain[k0 + kk]; scr[kk * 33 + (lane & 31)] = v; }
.LBB0_144:
	v_lshl_add_u64 v[58:59], v[54:55], 0, s[30:31]
	global_load_dword v58, v[58:59], off nt
	v_cndmask_b32_e64 v59, 0, 1, s[12:13]
	v_cmp_ne_u32_e64 s[4:5], 1, v59
	v_lshl_add_u64 v[100:101], v[52:53], 0, s[30:31]
	global_load_dword v100, v[100:101], off nt
	v_lshl_add_u64 v[98:99], s[36:37], 0, v[24:25]
	v_lshl_add_u64 v[104:105], v[50:51], 0, s[30:31]
	global_load_dword v103, v[104:105], off nt
	v_lshl_add_u64 v[108:109], v[48:49], 0, s[30:31]
	global_load_dword v106, v[108:109], off nt
	v_lshl_add_u64 v[112:113], v[46:47], 0, s[30:31]
	global_load_dword v111, v[112:113], off nt
	v_lshl_add_u64 v[116:117], v[44:45], 0, s[30:31]
	global_load_dword v114, v[116:117], off nt
	v_lshl_add_u64 v[120:121], v[42:43], 0, s[30:31]
	global_load_dword v119, v[120:121], off nt
	v_lshl_add_u64 v[124:125], v[40:41], 0, s[30:31]
	global_load_dword v122, v[124:125], off nt
	v_lshl_add_u64 v[128:129], v[38:39], 0, s[30:31]
	global_load_dword v127, v[128:129], off nt
	v_lshl_add_u64 v[132:133], v[36:37], 0, s[30:31]
	global_load_dword v130, v[132:133], off nt
	v_lshl_add_u64 v[136:137], v[34:35], 0, s[30:31]
	global_load_dword v135, v[136:137], off nt
	v_lshl_add_u64 v[140:141], v[32:33], 0, s[30:31]
	global_load_dword v138, v[140:141], off nt
	v_lshl_add_u64 v[144:145], v[30:31], 0, s[30:31]
	global_load_dword v143, v[144:145], off nt
	v_lshl_add_u64 v[148:149], v[28:29], 0, s[30:31]
	global_load_dword v146, v[148:149], off nt
	v_lshl_add_u64 v[152:153], v[26:27], 0, s[30:31]
	global_load_dword v151, v[152:153], off nt
	v_lshl_add_u64 v[158:159], v[22:23], 0, s[30:31]
	global_load_dword v156, v[158:159], off nt
	s_andn2_b64 vcc, exec, s[12:13]
	s_cbranch_vccnz .Lp0w3_a
	v_lshl_add_u64 v[84:85], s[36:37], 0, v[56:57]
	global_load_dword v59, v[84:85], off offset:-120
	global_load_dword v101, v[98:99], off offset:-112
	global_load_dword v102, v[98:99], off offset:-104
	global_load_dword v107, v[98:99], off offset:-96
	global_load_dword v110, v[98:99], off offset:-88
	global_load_dword v115, v[98:99], off offset:-80
	global_load_dword v118, v[98:99], off offset:-72
	global_load_dword v123, v[98:99], off offset:-64
	global_load_dword v126, v[98:99], off offset:-56
	global_load_dword v131, v[98:99], off offset:-48
	global_load_dword v134, v[98:99], off offset:-40
	global_load_dword v139, v[98:99], off offset:-32
	global_load_dword v142, v[98:99], off offset:-24
	global_load_dword v147, v[98:99], off offset:-16
	global_load_dword v150, v[98:99], off offset:-8
	global_load_dword v154, v[98:99], off
; __device__ __forceinline__ void conv_item(const float* W, int K, int N, bf16* WT, const float* gain, int mapmode, bool f16, LAS float* scr, int item, int lane) {
;     ...
; #pragma unroll 16
;     for (int i = 0; i < 32; ++i) { const int kk = 2 * i + (lane >> 5); float v = __builtin_nontemporal_load(W + (size_t)(k0 + kk) * N + n0 + (lane & 31)); if (gain) v *= gain[k0 + kk]; scr[kk * 33 + (lane & 31)] = v; }
;     asm volatile("s_waitcnt lgkmcnt(0)" ::: "memory");
.Lp0w3_a:
	s_add_u32 s30, s30, 0xb0000
	s_addc_u32 s31, s31, 0
	s_add_u32 s36, s36, 0x80
	s_addc_u32 s37, s37, 0
	v_lshl_add_u64 v[160:161], v[54:55], 0, s[30:31]
	global_load_dword v160, v[160:161], off nt
	v_cndmask_b32_e64 v161, 0, 1, s[12:13]
	v_cmp_ne_u32_e64 s[4:5], 1, v161
	v_lshl_add_u64 v[166:167], v[52:53], 0, s[30:31]
	global_load_dword v166, v[166:167], off nt
	v_lshl_add_u64 v[164:165], s[36:37], 0, v[24:25]
	v_lshl_add_u64 v[170:171], v[50:51], 0, s[30:31]
	global_load_dword v169, v[170:171], off nt
	v_lshl_add_u64 v[174:175], v[48:49], 0, s[30:31]
	global_load_dword v172, v[174:175], off nt
	v_lshl_add_u64 v[178:179], v[46:47], 0, s[30:31]
	global_load_dword v177, v[178:179], off nt
	v_lshl_add_u64 v[182:183], v[44:45], 0, s[30:31]
	global_load_dword v180, v[182:183], off nt
	v_lshl_add_u64 v[186:187], v[42:43], 0, s[30:31]
	global_load_dword v185, v[186:187], off nt
	v_lshl_add_u64 v[190:191], v[40:41], 0, s[30:31]
	global_load_dword v188, v[190:191], off nt
	v_lshl_add_u64 v[194:195], v[38:39], 0, s[30:31]
	global_load_dword v193, v[194:195], off nt
	v_lshl_add_u64 v[198:199], v[36:37], 0, s[30:31]
	global_load_dword v196, v[198:199], off nt
	v_lshl_add_u64 v[202:203], v[34:35], 0, s[30:31]
	global_load_dword v201, v[202:203], off nt
	v_lshl_add_u64 v[206:207], v[32:33], 0, s[30:31]
	global_load_dword v204, v[206:207], off nt
	v_lshl_add_u64 v[210:211], v[30:31], 0, s[30:31]
	global_load_dword v209, v[210:211], off nt
	v_lshl_add_u64 v[214:215], v[28:29], 0, s[30:31]
	global_load_dword v212, v[214:215], off nt
	v_lshl_add_u64 v[218:219], v[26:27], 0, s[30:31]
	global_load_dword v217, v[218:219], off nt
	v_lshl_add_u64 v[224:225], v[22:23], 0, s[30:31]
	global_load_dword v222, v[224:225], off nt
	s_andn2_b64 vcc, exec, s[12:13]
	s_cbranch_vccnz .Lp0w3_ng
	v_lshl_add_u64 v[162:163], s[36:37], 0, v[56:57]
	global_load_dword v161, v[162:163], off offset:-120
	global_load_dword v167, v[164:165], off offset:-112
	global_load_dword v168, v[164:165], off offset:-104
	global_load_dword v173, v[164:165], off offset:-96
	global_load_dword v176, v[164:165], off offset:-88
	global_load_dword v181, v[164:165], off offset:-80
	global_load_dword v184, v[164:165], off offset:-72
	global_load_dword v189, v[164:165], off offset:-64
	global_load_dword v192, v[164:165], off offset:-56
	global_load_dword v197, v[164:165], off offset:-48
	global_load_dword v200, v[164:165], off offset:-40
	global_load_dword v205, v[164:165], off offset:-32
	global_load_dword v208, v[164:165], off offset:-24
	global_load_dword v213, v[164:165], off offset:-16
	global_load_dword v216, v[164:165], off offset:-8
	global_load_dword v220, v[164:165], off
	s_waitcnt vmcnt(0)
	v_mul_f32_e32 v58, v58, v59
	v_mul_f32_e32 v100, v100, v101
	v_mul_f32_e32 v103, v103, v102
	v_mul_f32_e32 v106, v106, v107
	v_mul_f32_e32 v111, v111, v110
	v_mul_f32_e32 v114, v114, v115
	v_mul_f32_e32 v119, v119, v118
	v_mul_f32_e32 v122, v122, v123
	v_mul_f32_e32 v127, v127, v126
	v_mul_f32_e32 v130, v130, v131
	v_mul_f32_e32 v135, v135, v134
	v_mul_f32_e32 v138, v138, v139
	v_mul_f32_e32 v143, v143, v142
	v_mul_f32_e32 v146, v146, v147
	v_mul_f32_e32 v151, v151, v150
	v_mul_f32_e32 v156, v156, v154
	v_mul_f32_e32 v160, v160, v161
	v_mul_f32_e32 v166, v166, v167
	v_mul_f32_e32 v169, v169, v168
	v_mul_f32_e32 v172, v172, v173
	v_mul_f32_e32 v177, v177, v176
	v_mul_f32_e32 v180, v180, v181
	v_mul_f32_e32 v185, v185, v184
	v_mul_f32_e32 v188, v188, v189
	v_mul_f32_e32 v193, v193, v192
	v_mul_f32_e32 v196, v196, v197
	v_mul_f32_e32 v201, v201, v200
	v_mul_f32_e32 v204, v204, v205
	v_mul_f32_e32 v209, v209, v208
	v_mul_f32_e32 v212, v212, v213
	v_mul_f32_e32 v217, v217, v216
	v_mul_f32_e32 v222, v222, v220
.Lp0w3_ng:
	s_waitcnt vmcnt(0)
	ds_write_b32 v83, v58
	ds_write_b32 v83, v100 offset:264
	ds_write_b32 v83, v103 offset:528
	ds_write_b32 v83, v106 offset:792
	ds_write_b32 v83, v111 offset:1056
	ds_write_b32 v83, v114 offset:1320
	ds_write_b32 v83, v119 offset:1584
	ds_write_b32 v83, v122 offset:1848
	ds_write_b32 v83, v127 offset:2112
	ds_write_b32 v83, v130 offset:2376
	ds_write_b32 v83, v135 offset:2640
	ds_write_b32 v83, v138 offset:2904
	ds_write_b32 v83, v143 offset:3168
	ds_write_b32 v83, v146 offset:3432
	ds_write_b32 v83, v151 offset:3696
	ds_write_b32 v83, v156 offset:3960
	v_add_u32_e32 v83, 0x1080, v83
	ds_write_b32 v83, v160
	ds_write_b32 v83, v166 offset:264
	ds_write_b32 v83, v169 offset:528
	ds_write_b32 v83, v172 offset:792
	ds_write_b32 v83, v177 offset:1056
	ds_write_b32 v83, v180 offset:1320
	ds_write_b32 v83, v185 offset:1584
	ds_write_b32 v83, v188 offset:1848
	ds_write_b32 v83, v193 offset:2112
	ds_write_b32 v83, v196 offset:2376
	ds_write_b32 v83, v201 offset:2640
	ds_write_b32 v83, v204 offset:2904
	ds_write_b32 v83, v209 offset:3168
	ds_write_b32 v83, v212 offset:3432
	ds_write_b32 v83, v217 offset:3696
	ds_write_b32 v83, v222 offset:3960
	v_add_u32_e32 v83, 0x1080, v83
	s_add_u32 s30, s30, 0xb0000
	s_addc_u32 s31, s31, 0
	s_add_u32 s36, s36, 0x80
	s_addc_u32 s37, s37, 0
	s_branch .LBB0_176
